# v53 + rglru item set-up: gate-weight copy and table loads issued together, one wait (was ~10 serialized load round trips)
# speedup vs baseline: 1.0070x; 1.0026x over previous
.LBB0_345:
	v_mov_b32_e32 v50, v208
	s_bfe_u32 s12, s18, 0x40002
	s_mul_i32 s40, s12, 0x58
	v_readfirstlane_b32 s16, v50
	s_ashr_i32 s14, s16, 6
	s_bfe_u32 s19, s18, 0x10001
	s_ashr_i32 s17, s18, 6
	s_lshl_b32 s15, s40, 1
	s_add_u32 s78, s34, s15
	s_addc_u32 s79, s39, 0
	s_cmp_eq_u32 s19, 0
	s_cselect_b64 s[44:45], -1, 0
	v_and_b32_e32 v236, 15, v50
	s_lshl_b32 s85, s14, 5
	s_waitcnt vmcnt(0)
	v_bfe_u32 v122, v50, 4, 2
	v_or_b32_e32 v0, s85, v236
	v_sub_u32_e32 v2, 0xff, v0
	v_lshlrev_b32_e32 v237, 3, v122
	v_cndmask_b32_e64 v38, v2, v0, s[44:45]
	v_or_b32_e32 v12, 64, v237
	v_min_i32_e32 v0, 0x101, v38
	v_min_u32_e32 v12, 0x50, v12
	v_add_u32_e32 v0, -2, v0
	v_cmp_lt_i32_e32 vcc, 1, v38
	v_lshlrev_b32_e32 v174, 1, v12
	v_min_i32_e32 v12, 0x100, v38
	v_cndmask_b32_e32 v0, 0, v0, vcc
	v_add_u32_e32 v12, -1, v12
	v_cmp_lt_i32_e32 vcc, 0, v38
	v_min_i32_e32 v39, 0xfe, v38
	s_lshl_b32 s88, s17, 8
	v_cndmask_b32_e32 v12, 0, v12, vcc
	v_mov_b32_e32 v26, 0xff
	v_add_u32_e32 v39, 1, v39
	v_cmp_lt_i32_e32 vcc, -2, v38
	s_addk_i32 s88, 0x4000
	v_med3_i32 v26, v38, 0, v26
	v_cndmask_b32_e32 v38, 0, v39, vcc
	v_add_u32_e32 v0, s88, v0
	v_mov_b64_e32 v[34:35], s[78:79]
	v_add_u32_e32 v12, s88, v12
	v_or_b32_e32 v26, s88, v26
	v_add_u32_e32 v38, s88, v38
	v_mad_i64_i32 v[10:11], s[10:11], v0, s91, v[34:35]
	v_and_b32_e32 v0, 48, v50
	v_mov_b32_e32 v175, v1
	v_mad_i64_i32 v[18:19], s[10:11], v12, s91, v[34:35]
	v_mad_i64_i32 v[36:37], s[10:11], v26, s91, v[34:35]
	v_mad_i64_i32 v[42:43], s[10:11], v38, s91, v[34:35]
	v_lshl_add_u64 v[6:7], v[10:11], 0, v[0:1]
	v_lshl_add_u64 v[10:11], v[10:11], 0, v[174:175]
	v_lshl_add_u64 v[20:21], v[18:19], 0, v[0:1]
	v_lshl_add_u64 v[22:23], v[18:19], 0, v[174:175]
	v_lshl_add_u64 v[30:31], v[36:37], 0, v[0:1]
	v_lshl_add_u64 v[36:37], v[36:37], 0, v[174:175]
	v_lshl_add_u64 v[44:45], v[42:43], 0, v[0:1]
	v_lshl_add_u64 v[46:47], v[42:43], 0, v[174:175]
	global_load_dwordx4 v[2:5], v[6:7], off
	s_nop 0
	global_load_dwordx4 v[6:9], v[6:7], off offset:64
	s_nop 0
	global_load_dwordx4 v[10:13], v[10:11], off
	s_nop 0
	global_load_dwordx4 v[14:17], v[20:21], off
	s_nop 0
	global_load_dwordx4 v[18:21], v[20:21], off offset:64
	s_nop 0
	global_load_dwordx4 v[22:25], v[22:23], off
	s_nop 0
	global_load_dwordx4 v[26:29], v[30:31], off
	s_nop 0
	global_load_dwordx4 v[30:33], v[30:31], off offset:64
	s_nop 0
	global_load_dwordx4 v[34:37], v[36:37], off
	s_nop 0
	global_load_dwordx4 v[38:41], v[44:45], off
	s_nop 0
	global_load_dwordx4 v[42:45], v[44:45], off offset:64
	s_nop 0
	global_load_dwordx4 v[46:49], v[46:47], off
	s_movk_i32 s10, 0x480
	v_cmp_gt_i32_e32 vcc, s10, v50
	s_and_saveexec_b64 s[10:11], vcc
	s_mov_b64 s[46:47], 0x2000
	s_nop 0
	s_nop 0
	s_nop 0
	s_nop 0
	s_lshl_b32 s13, s19, 5
	s_add_i32 s36, s82, s13
	s_add_i32 s36, s36, s12
	s_mul_hi_i32 s37, s36, 0x4800
	s_mulk_i32 s36, 0x4800
	s_add_u32 s36, s70, s36
	s_addc_u32 s37, s71, s37
	s_add_i32 s13, s77, s13
	s_add_i32 s12, s13, s12
	s_mul_hi_i32 s13, s12, 0x4800
	s_mulk_i32 s12, 0x4800
	v_ashrrev_i32_e32 v51, 31, v50
	s_add_u32 s12, s70, s12
	v_lshlrev_b64 v[54:55], 4, v[50:51]
	s_addc_u32 s13, s71, s13
	v_lshl_add_u32 v97, v50, 4, 0
	v_lshl_add_u64 v[52:53], s[36:37], 0, v[54:55]
	v_lshl_add_u64 v[54:55], s[12:13], 0, v[54:55]
	global_load_dwordx4 v[58:61], v[54:55], off
	global_load_dwordx4 v[62:65], v[52:53], off
	v_lshl_add_u64 v[54:55], v[54:55], 0, s[46:47]
	v_lshl_add_u64 v[52:53], v[52:53], 0, s[46:47]
	global_load_dwordx4 v[66:69], v[54:55], off
	global_load_dwordx4 v[70:73], v[52:53], off
	v_cmp_gt_u32_e32 vcc, 0x80, v50
	s_and_saveexec_b64 s[12:13], vcc
	v_lshl_add_u64 v[54:55], v[54:55], 0, s[46:47]
	v_lshl_add_u64 v[52:53], v[52:53], 0, s[46:47]
	global_load_dwordx4 v[74:77], v[54:55], off
	global_load_dwordx4 v[78:81], v[52:53], off
	s_or_b64 exec, exec, s[12:13]
.LBB0_348:
	s_or_b64 exec, exec, s[10:11]
	v_and_b32_e32 v123, 63, v50
	v_cmp_gt_i32_e32 vcc, s95, v50
	v_lshl_add_u32 v51, v50, 2, 0
	s_and_saveexec_b64 s[10:11], vcc
	s_cbranch_execz .Lrgs_join
	s_or_b32 s12, s19, s20
	s_mul_i32 s19, s12, 0x580
	s_load_dwordx4 s[52:55], s[0:1], 0xc0
	s_load_dwordx2 s[12:13], s[0:1], 0xd8
	s_load_dwordx4 s[48:51], s[0:1], 0xe8
	v_min_i32_e32 v52, 0x57, v50
	v_add_u32_e32 v52, s40, v52
	s_waitcnt lgkmcnt(0)
	v_mov_b32_e32 v54, s52
	v_mov_b32_e32 v55, s53
	v_ashrrev_i32_e32 v53, 31, v52
	v_lshl_add_u64 v[54:55], v[52:53], 2, v[54:55]
	v_lshl_add_u64 v[98:99], v[54:55], 0, s[2:3]
	global_load_dword v86, v[98:99], off
	v_lshl_add_u64 v[98:99], v[54:55], 0, s[6:7]
	global_load_dword v87, v[98:99], off
	v_readlane_b32 s36, v255, 29
	v_mov_b32_e32 v56, s54
	v_mov_b32_e32 v57, s55
	v_readlane_b32 s37, v255, 30
	v_lshl_add_u64 v[98:99], v[54:55], 0, s[8:9]
	v_lshl_add_u64 v[54:55], v[54:55], 0, s[74:75]
	global_load_dword v88, v[98:99], off
	global_load_dword v89, v[54:55], off
	v_add_u32_e32 v54, s19, v52
	s_mul_i32 s19, s36, 0x580
	v_add_u32_e32 v52, s19, v52
	v_ashrrev_i32_e32 v53, 31, v52
	v_ashrrev_i32_e32 v55, 31, v54
	v_lshl_add_u64 v[52:53], v[52:53], 2, v[56:57]
	v_lshlrev_b64 v[54:55], 2, v[54:55]
	global_load_dword v90, v[52:53], off
	v_lshl_add_u64 v[52:53], s[12:13], 0, v[54:55]
	global_load_dword v91, v[52:53], off
	s_mov_b32 s12, 0xbfb8aa3b
	v_lshl_add_u64 v[52:53], s[48:49], 0, v[54:55]
	v_lshl_add_u64 v[54:55], s[50:51], 0, v[54:55]
	global_load_dword v52, v[52:53], off
	s_nop 0
	global_load_dword v53, v[54:55], off
.Lrgs_join:
	s_or_b64 exec, exec, s[10:11]
	s_waitcnt vmcnt(0)
	ds_write_b128 v97, v[58:61]
	ds_write_b128 v97, v[62:65] offset:18432
	ds_write_b128 v97, v[66:69] offset:8192
	ds_write_b128 v97, v[70:73] offset:26624
	v_cmp_gt_u32_e32 vcc, 0x80, v50
	s_and_saveexec_b64 s[10:11], vcc
	ds_write_b128 v97, v[74:77] offset:16384
	ds_write_b128 v97, v[78:81] offset:34816
	s_or_b64 exec, exec, s[10:11]
	v_cmp_gt_i32_e32 vcc, s95, v50
	s_and_saveexec_b64 s[10:11], vcc
	s_cbranch_execz .LBB0_350
	v_add_u32_e32 v94, 0x9000, v51
	v_add_u32_e32 v95, 0x9200, v51
	v_add_u32_e32 v96, 0x9400, v51
	ds_write2_b32 v94, v86, v87 offset1:96
	ds_write2_b32 v95, v88, v89 offset0:64 offset1:160
	ds_write2_b32 v96, v90, v91 offset0:128 offset1:224
	v_mul_f32_e32 v54, 0xbfb8aa3b, v53
	v_fma_f32 v55, v53, s12, -v54
	v_rndne_f32_e32 v56, v54
	v_fmac_f32_e32 v55, 0xb2a5705f, v53
	v_sub_f32_e32 v54, v54, v56
	v_add_f32_e32 v54, v54, v55
	v_exp_f32_e32 v54, v54
	v_cvt_i32_f32_e32 v55, v56
	s_mov_b32 s12, 0x42ce8ed0
	v_cmp_nlt_f32_e32 vcc, s12, v53
	s_mov_b32 s12, 0xc2b17218
	v_ldexp_f32 v54, v54, v55
	v_cndmask_b32_e32 v54, 0, v54, vcc
	v_cmp_ngt_f32_e32 vcc, s12, v53
	s_mov_b32 s12, 0x3f2aaaab
	s_nop 0
	v_cndmask_b32_e32 v53, v227, v54, vcc
	v_add_f32_e32 v56, 1.0, v53
	v_add_f32_e32 v54, -1.0, v56
	v_sub_f32_e32 v55, v54, v56
	v_add_f32_e32 v55, 1.0, v55
	v_sub_f32_e32 v54, v53, v54
	v_add_f32_e32 v57, v54, v55
	v_frexp_mant_f32_e32 v54, v56
	v_cmp_gt_f32_e32 vcc, s12, v54
	v_cvt_f64_f32_e32 v[54:55], v56
	v_frexp_exp_i32_f64_e32 v54, v[54:55]
	v_subbrev_co_u32_e32 v58, vcc, 0, v54, vcc
	v_sub_u32_e32 v54, 0, v58
	v_ldexp_f32 v55, v56, v54
	v_add_f32_e32 v56, -1.0, v55
	v_ldexp_f32 v54, v57, v54
	v_add_f32_e32 v57, 1.0, v56
	v_sub_f32_e32 v57, v55, v57
	v_add_f32_e32 v57, v54, v57
	v_add_f32_e32 v59, v56, v57
	v_sub_f32_e32 v56, v56, v59
	v_add_f32_e32 v56, v57, v56
	v_add_f32_e32 v57, 1.0, v55
	v_add_f32_e32 v60, -1.0, v57
	v_sub_f32_e32 v55, v55, v60
	v_add_f32_e32 v54, v54, v55
	v_add_f32_e32 v55, v57, v54
	v_sub_f32_e32 v57, v57, v55
	v_add_f32_e32 v54, v54, v57
	v_rcp_f32_e32 v57, v55
	v_cvt_f32_i32_e32 v58, v58
	s_mov_b32 s12, 0x3f317218
	v_mul_f32_e32 v60, v59, v57
	v_mul_f32_e32 v61, v55, v60
	v_fma_f32 v62, v60, v55, -v61
	v_fmac_f32_e32 v62, v60, v54
	v_add_f32_e32 v63, v61, v62
	v_sub_f32_e32 v64, v59, v63
	v_sub_f32_e32 v59, v59, v64
	v_sub_f32_e32 v61, v63, v61
	v_sub_f32_e32 v59, v59, v63
	v_add_f32_e32 v56, v56, v59
	v_sub_f32_e32 v59, v61, v62
	v_add_f32_e32 v56, v59, v56
	v_add_f32_e32 v59, v64, v56
	v_mul_f32_e32 v61, v57, v59
	v_mul_f32_e32 v62, v55, v61
	v_fma_f32 v55, v61, v55, -v62
	v_fmac_f32_e32 v55, v61, v54
	v_sub_f32_e32 v54, v64, v59
	v_add_f32_e32 v54, v56, v54
	v_add_f32_e32 v56, v62, v55
	v_sub_f32_e32 v63, v59, v56
	v_sub_f32_e32 v59, v59, v63
	v_sub_f32_e32 v62, v56, v62
	v_sub_f32_e32 v56, v59, v56
	v_add_f32_e32 v54, v54, v56
	v_sub_f32_e32 v55, v62, v55
	v_add_f32_e32 v54, v55, v54
	v_add_f32_e32 v56, v60, v61
	v_add_f32_e32 v54, v63, v54
	v_sub_f32_e32 v55, v56, v60
	v_mul_f32_e32 v54, v57, v54
	v_sub_f32_e32 v55, v61, v55
	v_add_f32_e32 v57, v55, v54
	v_mul_f32_e32 v60, 0x3f317218, v58
	v_add_f32_e32 v54, v56, v57
	v_fma_f32 v61, v58, s12, -v60
	v_mul_f32_e32 v55, v54, v54
	v_mov_b32_e32 v59, 0x3ecc95a3
	v_fmac_f32_e32 v61, 0xb102e308, v58
	v_sub_f32_e32 v56, v54, v56
	v_fmamk_f32 v59, v55, 0x3e9b6dac, v59
	v_sub_f32_e32 v56, v57, v56
	v_add_f32_e32 v57, v60, v61
	v_fmaak_f32 v59, v55, v59, 0x3f2aaada
	v_sub_f32_e32 v58, v57, v60
	v_ldexp_f32 v60, v54, 1
	v_mul_f32_e32 v54, v54, v55
	v_mul_f32_e32 v54, v54, v59
	v_add_f32_e32 v55, v60, v54
	v_sub_f32_e32 v59, v55, v60
	v_ldexp_f32 v56, v56, 1
	v_sub_f32_e32 v54, v54, v59
	v_add_f32_e32 v54, v56, v54
	v_add_f32_e32 v56, v55, v54
	v_sub_f32_e32 v55, v56, v55
	v_sub_f32_e32 v54, v54, v55
	v_add_f32_e32 v55, v57, v56
	v_sub_f32_e32 v59, v55, v57
	v_sub_f32_e32 v60, v55, v59
	v_sub_f32_e32 v58, v61, v58
	v_sub_f32_e32 v57, v57, v60
	v_sub_f32_e32 v56, v56, v59
	v_add_f32_e32 v56, v56, v57
	v_add_f32_e32 v57, v58, v54
	v_sub_f32_e32 v59, v57, v58
	v_add_f32_e32 v56, v57, v56
	v_sub_f32_e32 v60, v57, v59
	v_add_f32_e32 v57, v55, v56
	v_sub_f32_e32 v58, v58, v60
	v_sub_f32_e32 v54, v54, v59
	v_sub_f32_e32 v55, v57, v55
	v_add_f32_e32 v54, v54, v58
	v_sub_f32_e32 v55, v56, v55
	v_add_f32_e32 v54, v54, v55
	s_mov_b32 s12, 0x7f800000
	v_add_f32_e32 v54, v57, v54
	v_cmp_neq_f32_e32 vcc, s12, v53
	s_mov_b32 s12, 0x33800000
	s_nop 0
	v_cndmask_b32_e32 v54, v227, v54, vcc
	v_cmp_lt_f32_e64 vcc, |v53|, s12
	s_nop 1
	v_cndmask_b32_e32 v53, v54, v53, vcc
	v_mul_f32_e32 v53, 0xc138aa3b, v53
	v_add_u32_e32 v54, 0x9800, v51
	ds_write2_b32 v54, v52, v53 offset0:64 offset1:160
